# speedup vs baseline: 1.0465x; 1.0093x over previous
; __device__ void phase5(const Params& p, char* smem, int wave_s) {
;     ...
;   { const int ln = get_tid(wave_s) & 63;
;     float mq = fmaxf(fmaxf(fabsf(p.g_qk_q[ln]), fabsf(p.g_qk_q[64 + ln])), fabsf(p.g_qk_q[128 + ln]));
;     float mk = fmaxf(fmaxf(fabsf(p.g_qk_k[ln]), fabsf(p.g_qk_k[64 + ln])), fabsf(p.g_qk_k[128 + ln]));
; #pragma unroll
;     for (int o_ = 32; o_ > 0; o_ >>= 1) { mq = fmaxf(mq, __shfl_xor(mq, o_)); mk = fmaxf(mk, __shfl_xor(mk, o_)); }
;     negM = -(13.856406460551018f * 1.4426950408889634f * 1.03f) * mq * mk; }
;   const int xcd = blockIdx.x & 7, slot = blockIdx.x >> 3, per = NBLK >> 3;
;   for (int i = slot; i < NSEQ * NH; i += per) {
;     const int tid = get_tid(wave_s);
;     const int pair = xcd + 8 * (i >> 3), qb = i & 7, seq = pair >> 3, h = pair & 7;
.LBB0_715:
	s_or_b64 exec, exec, s[0:1]
	s_barrier
	v_mbcnt_lo_u32_b32 v0, -1, 0
	v_mbcnt_hi_u32_b32 v0, -1, v0
	s_cmpk_gt_u32 s2, 0x9ff
	v_and_b32_e32 v0, 63, v0
	v_lshlrev_b32_e32 v0, 2, v0
	global_load_dword v1, v0, s[52:53]
	global_load_dword v2, v0, s[52:53] offset:256
	global_load_dword v3, v0, s[52:53] offset:512
	global_load_dword v4, v0, s[54:55] offset:512
	global_load_dword v5, v0, s[54:55] offset:256
	global_load_dword v6, v0, s[54:55]
	v_mbcnt_hi_u32_b32 v0, -1, v200
	v_and_b32_e32 v7, 64, v0
	v_xor_b32_e32 v8, 32, v0
	v_add_u32_e32 v7, 64, v7
	v_cmp_lt_i32_e32 vcc, v8, v7
	v_xor_b32_e32 v9, 16, v0
	v_xor_b32_e32 v10, 8, v0
	v_cndmask_b32_e32 v8, v0, v8, vcc
	v_lshlrev_b32_e32 v200, 2, v8
	v_cmp_lt_i32_e32 vcc, v9, v7
	v_xor_b32_e32 v11, 4, v0
	v_xor_b32_e32 v12, 2, v0
	v_xor_b32_e32 v13, 1, v0
	s_mov_b32 s1, 0
	s_waitcnt vmcnt(3)
	v_max3_f32 v1, |v1|, |v2|, |v3|
	ds_bpermute_b32 v3, v200, v1
	s_waitcnt vmcnt(0)
	v_max3_f32 v2, |v6|, |v5|, |v4|
	ds_bpermute_b32 v4, v200, v2
	v_cndmask_b32_e32 v5, v0, v9, vcc
	s_waitcnt lgkmcnt(1)
	v_max_f32_e32 v3, v3, v3
	v_lshlrev_b32_e32 v201, 2, v5
	v_max_f32_e32 v1, v1, v3
	s_waitcnt lgkmcnt(0)
	v_max_f32_e32 v4, v4, v4
	v_max_f32_e32 v2, v2, v4
	ds_bpermute_b32 v3, v201, v1
	ds_bpermute_b32 v4, v201, v2
	v_cmp_lt_i32_e32 vcc, v10, v7
	s_waitcnt lgkmcnt(1)
	v_max_f32_e32 v3, v3, v3
	v_cndmask_b32_e32 v5, v0, v10, vcc
	s_waitcnt lgkmcnt(0)
	v_max_f32_e32 v4, v4, v4
	v_lshlrev_b32_e32 v202, 2, v5
	v_max_f32_e32 v1, v1, v3
	v_max_f32_e32 v2, v2, v4
	ds_bpermute_b32 v3, v202, v1
	ds_bpermute_b32 v4, v202, v2
	v_cmp_lt_i32_e32 vcc, v11, v7
	s_waitcnt lgkmcnt(1)
	v_max_f32_e32 v3, v3, v3
	v_cndmask_b32_e32 v5, v0, v11, vcc
	s_waitcnt lgkmcnt(0)
	v_max_f32_e32 v4, v4, v4
	v_lshlrev_b32_e32 v203, 2, v5
	v_max_f32_e32 v1, v1, v3
	v_max_f32_e32 v2, v2, v4
	ds_bpermute_b32 v3, v203, v1
	ds_bpermute_b32 v4, v203, v2
	v_cmp_lt_i32_e32 vcc, v12, v7
	s_waitcnt lgkmcnt(1)
	v_max_f32_e32 v3, v3, v3
	v_cndmask_b32_e32 v5, v0, v12, vcc
	s_waitcnt lgkmcnt(0)
	v_max_f32_e32 v4, v4, v4
	v_lshlrev_b32_e32 v204, 2, v5
	v_max_f32_e32 v1, v1, v3
	v_max_f32_e32 v2, v2, v4
	ds_bpermute_b32 v3, v204, v1
	ds_bpermute_b32 v4, v204, v2
	v_cmp_lt_i32_e32 vcc, v13, v7
	s_nop 1
	v_cndmask_b32_e32 v0, v0, v13, vcc
	v_lshlrev_b32_e32 v205, 2, v0
	s_waitcnt lgkmcnt(1)
	v_max_f32_e32 v0, v3, v3
	s_waitcnt lgkmcnt(0)
	v_max_f32_e32 v3, v4, v4
	v_max_f32_e32 v0, v1, v0
	v_max_f32_e32 v2, v2, v3
	ds_bpermute_b32 v1, v205, v0
	ds_bpermute_b32 v3, v205, v2
	s_cbranch_scc1 .LBB0_722
	s_and_b32 s0, s2, 7
	s_lshr_b32 s56, s2, 3
	s_mul_i32 s4, s0, 0x180
	s_add_u32 s57, s6, s4
	s_addc_u32 s58, s7, 0
	s_lshl_b32 s4, s0, 8
	s_lshl_b32 s59, s0, 9
	s_add_u32 s61, s50, s59
	s_waitcnt lgkmcnt(1)
	v_max_f32_e32 v1, v1, v1
	v_max_f32_e32 v0, v0, v0
	s_addc_u32 s62, s51, 0
	s_lshl_b32 s63, s0, 7
	s_waitcnt lgkmcnt(0)
	v_max_f32_e32 v3, v3, v3
	v_max_f32_e32 v2, v2, v2
	v_max_f32_e32 v0, v0, v1
	s_add_u32 s65, s44, s63
	v_max_f32_e32 v2, v2, v3
	v_mul_f32_e32 v0, 0xc1a4b8e7, v0
	s_addc_u32 s66, s45, 0
	v_mul_f32_e32 v0, v2, v0
	s_add_u32 s67, s30, s4
	s_mov_b32 s60, s1
	s_mov_b32 s64, s1
	s_addc_u32 s70, s31, 0
	v_mov_b32_e32 v1, v0
	v_mov_b32_e32 v2, v0
	v_mov_b32_e32 v3, v0
	v_mov_b32_e32 v4, v0
	v_mov_b32_e32 v5, v0
	v_mov_b32_e32 v6, v0
	v_mov_b32_e32 v7, v0
	v_mov_b32_e32 v8, v0
	v_mov_b32_e32 v9, v0
	v_mov_b32_e32 v10, v0
	v_mov_b32_e32 v11, v0
	v_mov_b32_e32 v12, v0
	v_mov_b32_e32 v13, v0
	v_mov_b32_e32 v14, v0
	v_mov_b32_e32 v15, v0
	v_mbcnt_lo_u32_b32 v252, -1, 0
	v_mbcnt_hi_u32_b32 v252, -1, v252
	v_lshlrev_b32_e32 v253, 4, v252
	v_cmp_gt_u32_e32 vcc, 48, v252
	s_and_saveexec_b64 s[90:91], vcc
	global_load_dwordx4 v[248:251], v253, s[52:53]
	v_add_u32_e32 v253, 0x1e800, v253
	s_waitcnt vmcnt(0)
	ds_write_b128 v253, v[248:251]
	s_waitcnt lgkmcnt(0)
	s_or_b64 exec, exec, s[90:91]
	s_lshl_b32 s71, s56, 8
	s_movk_i32 s72, 0xc00
	s_movk_i32 s73, 0xc0
	s_movk_i32 s74, 0xf0
	s_movk_i32 s75, 0x70
	v_mov_b32_e32 v177, 0
	s_mov_b64 s[4:5], 0x100
	s_movk_i32 s76, 0xffe0
	s_mov_b64 s[10:11], 0x40000
	s_mov_b64 s[12:13], 0x40040
	s_mov_b32 s77, 0x800000
	s_mov_b32 s78, 0x40000
	s_mov_b64 s[14:15], 0x10000
	s_mov_b64 s[16:17], 0x16a80000
	s_mov_b64 s[18:19], 0x2aa20000
	s_mov_b64 s[20:21], 0x16a80100
	s_mov_b64 s[22:23], 0x16ac0000
	s_mov_b64 s[40:41], 0x2aa30000
	s_mov_b64 s[42:43], 0x16ac0100
	s_mov_b64 s[44:45], 0x20000
	s_mov_b64 s[46:47], 0x80000
	s_branch .LBB0_718

; __device__ __forceinline__ float bflo(unsigned w) { return __uint_as_float(w << 16); }
; __device__ __forceinline__ float bfhi(unsigned w) { return __uint_as_float(w & 0xffff0000u); }
; #define AISSUE(k0, soff) do { const char* kb_ = (const char*)Kn + (size_t)(k0) * 4096; const char* rb_ = (const char*)Kr + (size_t)(k0) * 1024; \
;     char* st_ = lds + (soff) + tid * 16; \
;     GLDS(kb_ + vkn0, st_ + KOFF); GLDS(kb_ + vkn1, st_ + KOFF + 8192); GLDS(rb_ + vkr, st_ + KOFF + KROPE_OFF); \
;     GLDS(kb_ + vv0, st_); GLDS(kb_ + vv1, st_ + 8192); } while (0)
; __device__ __forceinline__ void attn_body(const u16* __restrict__ Qb, const u16* __restrict__ Kn, const u16* __restrict__ Kr,
;                                           u16* __restrict__ Ob, char* lds, int tid, const float* __restrict__ gq_, const float* __restrict__ tab_, int qpos0, float negM) {
;   const int wid = tid >> 6, lane = tid & 63, r32 = lane & 31, hi = lane >> 5;
;   float* wsp = (float*)(lds + 3 * 40960) + wid * 64; float* li_l = wsp;
;   float l_reg = 0; f32x16 o[4] = {}; bf16x8 qr[12];
;   unsigned vkn0, vkn1, vkr, vv0, vv1;
;   { int sl = tid;        int row = sl >> 4, c = (sl & 15) ^ (row & 15);        vkn0 = (unsigned)(row * 4096 + c * 16);
;     sl = tid + 512;      row = sl >> 4;     c = (sl & 15) ^ (row & 15);        vkn1 = (unsigned)(row * 4096 + c * 16);
;     row = tid >> 3;      c = (tid & 7) ^ ((row >> 1) & 7);                     vkr  = (unsigned)(row * 1024 + c * 16);
; #pragma unroll
;     for (int i = 0; i < 2; ++i) { const int o = (tid + i * 512) * 16, sub = o >> 9, within = o & 511;
;       const int kk = (sub >> 2) * 8 + (within >> 6), cc = (sub & 3) * 32 + ((within & 63) >> 1);
;       const int k = (kk & ~0xC) | ((kk & 4) << 1) | ((kk & 8) >> 1);
;       const unsigned v = (unsigned)(k * 4096 + cc * 2 + 256);
;       if (i == 0) vv0 = v; else vv1 = v; } }
;   constexpr int STG = 40960, KOFF = 16384;
;     ...
;   AISSUE(0, 0);
;   {
;     const char* Qw = (const char*)Qb + (unsigned)(((wid * 32 + r32) * 1536 + hi * 8) * 2);
;     u32x4 qw[12];
; #pragma unroll
;     for (int d0 = 0; d0 < 12; ++d0) qw[d0] = *reinterpret_cast<const u32x4*>(Qw + d0 * 32);
;     float ss = 0.f;
; #pragma unroll
;     for (int d0 = 0; d0 < 12; ++d0)
; #pragma unroll
;       for (int e = 0; e < 4; ++e) { const float a = bflo(qw[d0][e]), b = bfhi(qw[d0][e]); ss += a * a + b * b; }
.LBB0_718:
	s_lshl_b32 s87, s3, 4
	s_lshl_b32 s0, s71, 10
	s_and_b32 s80, s0, 0x7e00000
	s_lshl_b32 s0, s71, 12
	v_mbcnt_lo_u32_b32 v96, -1, 0
	v_mbcnt_hi_u32_b32 v96, -1, v96
	s_and_b32 s79, s0, 0x1f800000
	v_or_b32_e32 v210, s3, v96
	s_lshl_b32 s0, s56, 8
	v_ashrrev_i32_e32 v20, 1, v210
	s_and_b32 s54, s0, 0x1f800
	s_mul_i32 s48, s56, 0xc0000
	v_bfi_b32 v66, s76, v20, v96
	s_mul_hi_u32 s49, s0, 0xc00
	s_add_u32 s50, s57, s48
	v_bfe_u32 v207, v96, 5, 1
	v_mul_lo_u32 v21, v66, s72
	s_addc_u32 s51, s58, s49
	v_lshl_or_b32 v67, v207, 4, v21
	s_barrier
	global_load_dwordx4 v[24:27], v67, s[50:51]
	v_lshlrev_b32_e32 v211, 4, v210
	v_bfe_u32 v23, v210, 2, 2
	v_lshrrev_b32_e32 v28, 1, v210
	v_and_or_b32 v23, v28, 8, v23
	v_lshlrev_b32_e32 v28, 1, v210
	v_and_b32_e32 v29, 48, v211
	v_and_or_b32 v38, v28, s73, v29
	v_bfe_i32 v28, v210, 4, 24
	v_and_b32_e32 v29, 0xffff0, v28
	v_lshrrev_b32_e32 v28, 1, v28
	v_and_b32_e32 v28, 4, v28
	v_or3_b32 v28, v29, v28, v23
	v_lshlrev_b32_e32 v36, 12, v28
	global_load_dwordx4 v[28:31], v67, s[50:51] offset:32
	global_load_dwordx4 v[42:45], v67, s[50:51] offset:64
	global_load_dwordx4 v[46:49], v67, s[50:51] offset:96
	v_add_u32_e32 v50, 0x2000, v211
	v_ashrrev_i32_e32 v33, 8, v50
	v_ashrrev_i32_e32 v16, 4, v210
	v_add_u32_e32 v18, 0x200, v210
	v_and_b32_e32 v34, 0xffff0, v33
	v_lshrrev_b32_e32 v33, 1, v33
	v_xor_b32_e32 v17, v16, v96
	v_ashrrev_i32_e32 v18, 4, v18
	v_and_b32_e32 v33, 4, v33
	v_lshlrev_b32_e32 v17, 4, v17
	v_xor_b32_e32 v19, v18, v96
	v_or3_b32 v23, v34, v33, v23
	v_lshlrev_b32_e32 v16, 12, v16
	v_lshlrev_b32_e32 v19, 4, v19
	v_lshlrev_b32_e32 v21, 7, v210
	v_or_b32_e32 v32, 0x100, v38
	v_lshlrev_b32_e32 v23, 12, v23
	v_and_or_b32 v176, v17, s74, v16
	v_lshlrev_b32_e32 v16, 12, v18
	v_bitop3_b32 v22, v211, v96, s3 bitop3:0x1e
	v_or_b32_e32 v80, v36, v32
	v_or_b32_e32 v81, v23, v32
	v_and_or_b32 v32, v19, s74, v16
	v_and_b32_e32 v16, 0xfffffc00, v21
	s_lshl_b32 s48, s54, 12
	v_and_or_b32 v34, v22, s75, v16
	v_add_u32_e32 v16, 0x4000, v211
	s_add_u32 s48, s61, s48
	v_readfirstlane_b32 s82, v16
	v_add_u32_e32 v16, 0x6000, v211
	s_addc_u32 s49, s62, 0
	s_lshl_b32 s54, s54, 10
	s_mov_b32 m0, s82
	v_readfirstlane_b32 s82, v16
	v_add_u32_e32 v16, 0x8000, v211
	s_add_u32 s54, s65, s54
	global_load_lds_dwordx4 v176, s[48:49]
	s_mov_b32 m0, s82
	v_readfirstlane_b32 s82, v16
	s_addc_u32 s55, s66, 0
	global_load_lds_dwordx4 v32, s[48:49]
	v_mov_b32_e32 v35, v177
	s_mov_b32 m0, s82
	v_or_b32_e32 v36, v38, v36
	v_mov_b32_e32 v37, v177
	v_lshl_add_u64 v[40:41], s[54:55], 0, v[34:35]
	global_load_lds_dwordx4 v34, s[54:55]
	v_lshl_add_u64 v[16:17], s[48:49], 0, v[36:37]
	v_readfirstlane_b32 s54, v211
	v_lshl_add_u64 v[16:17], v[16:17], 0, s[4:5]
	s_mov_b32 m0, s54
	v_or_b32_e32 v38, v38, v23
	v_mov_b32_e32 v39, v177
	global_load_lds_dwordx4 v[16:17], off
	v_lshl_add_u64 v[16:17], s[48:49], 0, v[38:39]
	v_readfirstlane_b32 s54, v50
	v_lshl_add_u64 v[16:17], v[16:17], 0, s[4:5]
	s_mov_b32 m0, s54
	v_and_b32_e32 v208, 0xffffffe0, v20
	global_load_lds_dwordx4 v[16:17], off
	global_load_dwordx4 v[50:53], v67, s[50:51] offset:128
	global_load_dwordx4 v[54:57], v67, s[50:51] offset:160
	global_load_dwordx4 v[58:61], v67, s[50:51] offset:192
	global_load_dwordx4 v[62:65], v67, s[50:51] offset:224
	s_nop 0
	global_load_dwordx4 v[16:19], v67, s[50:51] offset:256
	global_load_dwordx4 v[68:71], v67, s[50:51] offset:288
	global_load_dwordx4 v[20:23], v67, s[50:51] offset:320
	global_load_dwordx4 v[72:75], v67, s[50:51] offset:352
	s_waitcnt vmcnt(0)
	v_and_b32_e32 v133, 0xffff0000, v24
	v_and_b32_e32 v155, 0xffff0000, v25
	v_lshlrev_b32_e32 v132, 16, v24
	v_mul_f32_e32 v24, v133, v133
	v_lshlrev_b32_e32 v154, 16, v25
	v_mul_f32_e32 v25, v155, v155
	v_fmac_f32_e32 v24, v132, v132
	v_fmac_f32_e32 v25, v154, v154
	v_and_b32_e32 v163, 0xffff0000, v26
	v_add_f32_e32 v24, v24, v25
	v_lshlrev_b32_e32 v162, 16, v26
	v_mul_f32_e32 v25, v163, v163
	v_fmac_f32_e32 v25, v162, v162
	v_and_b32_e32 v165, 0xffff0000, v27
	v_add_f32_e32 v24, v25, v24
	v_lshlrev_b32_e32 v164, 16, v27
	v_mul_f32_e32 v25, v165, v165
	v_fmac_f32_e32 v25, v164, v164
	v_and_b32_e32 v167, 0xffff0000, v28
	v_add_f32_e32 v24, v25, v24
	v_lshlrev_b32_e32 v166, 16, v28
	v_mul_f32_e32 v25, v167, v167
	v_fmac_f32_e32 v25, v166, v166
	v_and_b32_e32 v169, 0xffff0000, v29
	v_add_f32_e32 v24, v25, v24
	v_lshlrev_b32_e32 v168, 16, v29
	v_mul_f32_e32 v25, v169, v169
	v_fmac_f32_e32 v25, v168, v168
	v_and_b32_e32 v125, 0xffff0000, v30
	v_add_f32_e32 v24, v25, v24
	v_lshlrev_b32_e32 v126, 16, v30
	v_mul_f32_e32 v25, v125, v125
	v_fmac_f32_e32 v25, v126, v126
	v_and_b32_e32 v127, 0xffff0000, v31
	v_add_f32_e32 v24, v25, v24
	v_lshlrev_b32_e32 v170, 16, v31
	v_mul_f32_e32 v25, v127, v127
	v_fmac_f32_e32 v25, v170, v170
	v_and_b32_e32 v172, 0xffff0000, v42
	v_add_f32_e32 v24, v25, v24
	v_lshlrev_b32_e32 v171, 16, v42
	v_mul_f32_e32 v25, v172, v172
	v_fmac_f32_e32 v25, v171, v171
	v_and_b32_e32 v174, 0xffff0000, v43
	v_add_f32_e32 v24, v25, v24
	v_lshlrev_b32_e32 v173, 16, v43
	v_mul_f32_e32 v25, v174, v174
	v_fmac_f32_e32 v25, v173, v173
	v_and_b32_e32 v178, 0xffff0000, v44
	v_add_f32_e32 v24, v25, v24
	v_lshlrev_b32_e32 v175, 16, v44
	v_mul_f32_e32 v25, v178, v178
	v_fmac_f32_e32 v25, v175, v175
	v_and_b32_e32 v117, 0xffff0000, v45
	v_add_f32_e32 v24, v25, v24
	v_lshlrev_b32_e32 v118, 16, v45
	v_mul_f32_e32 v25, v117, v117
	v_fmac_f32_e32 v25, v118, v118
	v_and_b32_e32 v119, 0xffff0000, v46
	v_add_f32_e32 v24, v25, v24
	v_lshlrev_b32_e32 v120, 16, v46
	v_mul_f32_e32 v25, v119, v119
	v_fmac_f32_e32 v25, v120, v120
	v_and_b32_e32 v121, 0xffff0000, v47
	v_add_f32_e32 v24, v25, v24
; __device__ __forceinline__ float bflo(unsigned w) { return __uint_as_float(w << 16); }
; __device__ __forceinline__ float bfhi(unsigned w) { return __uint_as_float(w & 0xffff0000u); }
; __device__ __forceinline__ void attn_body(const u16* __restrict__ Qb, const u16* __restrict__ Kn, const u16* __restrict__ Kr,
;                                           u16* __restrict__ Ob, char* lds, int tid, const float* __restrict__ gq_, const float* __restrict__ tab_, int qpos0, float negM) {
;     ...
;     for (int d0 = 0; d0 < 12; ++d0)
; #pragma unroll
;       for (int e = 0; e < 4; ++e) { const float a = bflo(qw[d0][e]), b = bfhi(qw[d0][e]); ss += a * a + b * b; }
;     { auto rr = __builtin_amdgcn_permlane32_swap(__float_as_uint(ss), __float_as_uint(ss), false, false);
;       ss = __uint_as_float(rr[0]) + __uint_as_float(rr[1]); }
;     const float rq = rsqrtf(ss * (1.f / 192.f) + EPS) * QSCALE;
;     const float* gq = gq_ + hi * 8;
; #pragma unroll
;     for (int d0 = 0; d0 < 8; ++d0) {
;       const f32x4 g0 = *reinterpret_cast<const f32x4*>(gq + d0 * 16), g1 = *reinterpret_cast<const f32x4*>(gq + d0 * 16 + 4);
;       const u32x4 w = qw[d0];
;       const u32x4 o = {cvtpk(bflo(w[0]) * rq * g0[0], bfhi(w[0]) * rq * g0[1]), cvtpk(bflo(w[1]) * rq * g0[2], bfhi(w[1]) * rq * g0[3]),
;                        cvtpk(bflo(w[2]) * rq * g1[0], bfhi(w[2]) * rq * g1[1]), cvtpk(bflo(w[3]) * rq * g1[2], bfhi(w[3]) * rq * g1[3])};
;       qr[d0] = *reinterpret_cast<const bf16x8*>(&o); }
	v_lshlrev_b32_e32 v122, 16, v47
	v_mul_f32_e32 v25, v121, v121
	v_fmac_f32_e32 v25, v122, v122
	v_and_b32_e32 v123, 0xffff0000, v48
	v_add_f32_e32 v24, v25, v24
	v_lshlrev_b32_e32 v124, 16, v48
	v_mul_f32_e32 v25, v123, v123
	v_fmac_f32_e32 v25, v124, v124
	v_and_b32_e32 v110, 0xffff0000, v49
	v_add_f32_e32 v24, v25, v24
	v_lshlrev_b32_e32 v111, 16, v49
	v_mul_f32_e32 v25, v110, v110
	v_fmac_f32_e32 v25, v111, v111
	v_and_b32_e32 v112, 0xffff0000, v50
	v_add_f32_e32 v24, v25, v24
	v_lshlrev_b32_e32 v113, 16, v50
	v_mul_f32_e32 v25, v112, v112
	v_fmac_f32_e32 v25, v113, v113
	v_and_b32_e32 v114, 0xffff0000, v51
	v_add_f32_e32 v24, v25, v24
	v_lshlrev_b32_e32 v115, 16, v51
	v_mul_f32_e32 v25, v114, v114
	v_fmac_f32_e32 v25, v115, v115
	v_and_b32_e32 v90, 0xffff0000, v52
	v_add_f32_e32 v24, v25, v24
	v_lshlrev_b32_e32 v116, 16, v52
	v_mul_f32_e32 v25, v90, v90
	v_fmac_f32_e32 v25, v116, v116
	v_and_b32_e32 v94, 0xffff0000, v53
	v_add_f32_e32 v24, v25, v24
	v_lshlrev_b32_e32 v98, 16, v53
	v_mul_f32_e32 v25, v94, v94
	v_fmac_f32_e32 v25, v98, v98
	v_and_b32_e32 v99, 0xffff0000, v54
	v_add_f32_e32 v24, v25, v24
	v_lshlrev_b32_e32 v103, 16, v54
	v_mul_f32_e32 v25, v99, v99
	v_fmac_f32_e32 v25, v103, v103
	v_and_b32_e32 v104, 0xffff0000, v55
	v_add_f32_e32 v24, v25, v24
	v_lshlrev_b32_e32 v106, 16, v55
	v_mul_f32_e32 v25, v104, v104
	v_fmac_f32_e32 v25, v106, v106
	v_and_b32_e32 v107, 0xffff0000, v56
	v_add_f32_e32 v24, v25, v24
	v_lshlrev_b32_e32 v108, 16, v56
	v_mul_f32_e32 v25, v107, v107
	v_fmac_f32_e32 v25, v108, v108
	v_and_b32_e32 v82, 0xffff0000, v57
	v_add_f32_e32 v24, v25, v24
	v_lshlrev_b32_e32 v109, 16, v57
	v_mul_f32_e32 v25, v82, v82
	v_fmac_f32_e32 v25, v109, v109
	v_and_b32_e32 v83, 0xffff0000, v58
	v_add_f32_e32 v24, v25, v24
	v_lshlrev_b32_e32 v84, 16, v58
	v_mul_f32_e32 v25, v83, v83
	v_fmac_f32_e32 v25, v84, v84
	v_and_b32_e32 v85, 0xffff0000, v59
	v_add_f32_e32 v24, v25, v24
	v_lshlrev_b32_e32 v86, 16, v59
	v_mul_f32_e32 v25, v85, v85
	v_fmac_f32_e32 v25, v86, v86
	v_and_b32_e32 v87, 0xffff0000, v60
	v_add_f32_e32 v24, v25, v24
	v_lshlrev_b32_e32 v88, 16, v60
	v_mul_f32_e32 v25, v87, v87
	v_fmac_f32_e32 v25, v88, v88
	v_and_b32_e32 v89, 0xffff0000, v61
	v_add_f32_e32 v24, v25, v24
	v_lshlrev_b32_e32 v91, 16, v61
	v_mul_f32_e32 v25, v89, v89
	v_fmac_f32_e32 v25, v91, v91
	v_and_b32_e32 v92, 0xffff0000, v62
	v_add_f32_e32 v24, v25, v24
	v_lshlrev_b32_e32 v95, 16, v62
	v_mul_f32_e32 v25, v92, v92
	v_fmac_f32_e32 v25, v95, v95
	v_and_b32_e32 v93, 0xffff0000, v63
	v_add_f32_e32 v24, v25, v24
	v_lshlrev_b32_e32 v100, 16, v63
	v_mul_f32_e32 v25, v93, v93
	v_fmac_f32_e32 v25, v100, v100
	v_and_b32_e32 v97, 0xffff0000, v64
	v_add_f32_e32 v24, v25, v24
	v_lshlrev_b32_e32 v101, 16, v64
	v_mul_f32_e32 v25, v97, v97
	v_fmac_f32_e32 v25, v101, v101
	v_and_b32_e32 v102, 0xffff0000, v65
	v_add_f32_e32 v24, v25, v24
	v_lshlrev_b32_e32 v105, 16, v65
	v_mul_f32_e32 v25, v102, v102
	v_fmac_f32_e32 v25, v105, v105
	v_and_b32_e32 v58, 32, v96
	v_add_u32_e32 v254, 0x1e800, v58
	v_add_f32_e32 v146, v25, v24
	ds_read_b128 v[24:27], v254 offset:16
	ds_read_b128 v[28:31], v254
	ds_read_b128 v[134:137], v254 offset:80
	ds_read_b128 v[138:141], v254 offset:64
	s_and_b32 s81, s0, 0x700
	v_add_u32_e32 v42, s81, v66
	v_ashrrev_i32_e32 v43, 31, v42
	v_lshlrev_b64 v[42:43], 7, v[42:43]
	v_lshl_add_u64 v[66:67], s[8:9], 0, v[42:43]
	v_and_b32_e32 v42, 0xffff0000, v75
	v_and_b32_e32 v46, 0xffff0000, v74
	v_lshlrev_b32_e32 v44, 16, v75
	v_lshlrev_b32_e32 v48, 16, v74
	v_mov_b32_e32 v52, v42
	v_mov_b32_e32 v53, v46
	v_mov_b32_e32 v50, v44
	v_mov_b32_e32 v51, v48
	v_pk_mul_f32 v[52:53], v[52:53], v[52:53]
	v_and_b32_e32 v54, 0xffff0000, v72
	v_pk_fma_f32 v[78:79], v[50:51], v[50:51], v[52:53]
	v_and_b32_e32 v50, 0xffff0000, v73
	v_lshlrev_b32_e32 v52, 16, v73
	v_lshlrev_b32_e32 v56, 16, v72
	v_mov_b32_e32 v62, v50
	v_mov_b32_e32 v63, v54
	v_mov_b32_e32 v60, v52
	v_mov_b32_e32 v61, v56
	v_pk_mul_f32 v[62:63], v[62:63], v[62:63]
	v_lshlrev_b32_e32 v53, 16, v69
	v_and_b32_e32 v51, 0xffff0000, v69
	v_lshlrev_b32_e32 v57, 16, v68
	v_and_b32_e32 v55, 0xffff0000, v68
	v_pk_fma_f32 v[68:69], v[60:61], v[60:61], v[62:63]
	v_and_b32_e32 v60, 0xffff0000, v23
	v_lshlrev_b32_e32 v64, 16, v22
	v_and_b32_e32 v22, 0xffff0000, v22
	v_lshlrev_b32_e32 v45, 16, v71
	v_and_b32_e32 v43, 0xffff0000, v71
	v_lshlrev_b32_e32 v49, 16, v70
	v_and_b32_e32 v47, 0xffff0000, v70
	v_lshlrev_b32_e32 v62, 16, v23
	v_mov_b32_e32 v70, v60
	v_mov_b32_e32 v71, v22
	v_lshlrev_b32_e32 v63, 16, v19
	v_and_b32_e32 v61, 0xffff0000, v19
	v_lshlrev_b32_e32 v65, 16, v18
	v_and_b32_e32 v23, 0xffff0000, v18
	v_mov_b32_e32 v18, v62
	v_mov_b32_e32 v19, v64
	v_pk_mul_f32 v[70:71], v[70:71], v[70:71]
	v_and_b32_e32 v75, 0xffff0000, v16
	v_and_b32_e32 v74, 0xffff0000, v20
	v_pk_fma_f32 v[128:129], v[18:19], v[18:19], v[70:71]
	v_lshlrev_b32_e32 v72, 16, v21
	v_and_b32_e32 v71, 0xffff0000, v17
	v_and_b32_e32 v70, 0xffff0000, v21
	v_lshlrev_b32_e32 v77, 16, v16
	v_lshlrev_b32_e32 v76, 16, v20
	v_pk_mul_f32 v[20:21], v[74:75], v[74:75]
	v_lshlrev_b32_e32 v73, 16, v17
	v_pk_mul_f32 v[18:19], v[70:71], v[70:71]
	v_pk_fma_f32 v[20:21], v[76:77], v[76:77], v[20:21]
	v_mul_f32_e32 v152, v65, v65
	v_pk_fma_f32 v[130:131], v[72:73], v[72:73], v[18:19]
	v_add_f32_e32 v21, v21, v146
	v_mul_f32_e32 v151, v63, v63
	v_fmac_f32_e32 v152, v23, v23
	v_add_f32_e32 v21, v131, v21
	v_mul_f32_e32 v150, v57, v57
	v_fmac_f32_e32 v151, v61, v61
	v_add_f32_e32 v21, v152, v21
	v_mul_f32_e32 v149, v53, v53
	v_fmac_f32_e32 v150, v55, v55
	v_add_f32_e32 v21, v151, v21
	v_mul_f32_e32 v148, v49, v49
	v_fmac_f32_e32 v149, v51, v51
	v_add_f32_e32 v21, v150, v21
	v_mul_f32_e32 v147, v45, v45
	v_fmac_f32_e32 v148, v47, v47
	v_add_f32_e32 v21, v149, v21
	v_fmac_f32_e32 v147, v43, v43
	v_add_f32_e32 v21, v148, v21
	v_add_f32_e32 v21, v147, v21
	v_add_f32_e32 v20, v20, v21
	v_add_f32_e32 v20, v130, v20
	v_add_f32_e32 v20, v129, v20
	v_add_f32_e32 v20, v128, v20
	v_add_f32_e32 v20, v69, v20
	v_add_f32_e32 v20, v68, v20
	v_add_f32_e32 v20, v79, v20
	v_add_f32_e32 v20, v78, v20
	v_mov_b32_e32 v21, v20
	s_nop 1
	v_permlane32_swap_b32_e32 v20, v21
	ds_read_b128 v[16:19], v254 offset:144
	ds_read_b128 v[142:145], v254 offset:128
	v_add_f32_e32 v20, v20, v21
	v_mov_b32_e32 v21, 0x358637bd
	v_fmamk_f32 v20, v20, 0x3baaaaab, v21
	v_mul_f32_e32 v21, 0x4b800000, v20
	v_cmp_gt_f32_e32 vcc, s77, v20
	ds_read_b128 v[146:149], v254 offset:208
	ds_read_b128 v[150:153], v254 offset:192
	v_cndmask_b32_e32 v20, v20, v21, vcc
	v_rsq_f32_e32 v20, v20
	v_mov_b32_e32 v59, v177
	v_lshl_add_u64 v[68:69], v[66:67], 0, v[58:59]
	v_lshl_add_u64 v[78:79], v[68:69], 0, s[10:11]
	v_mul_f32_e32 v21, 0x45800000, v20
	v_cndmask_b32_e32 v20, v20, v21, vcc
	v_mul_f32_e32 v20, 0x3dd53b94, v20
	v_mul_f32_e32 v21, v20, v132
	s_waitcnt vmcnt(0) lgkmcnt(0)
; __device__ __forceinline__ float bflo(unsigned w) { return __uint_as_float(w << 16); }
; __device__ __forceinline__ float bfhi(unsigned w) { return __uint_as_float(w & 0xffff0000u); }
; __device__ __forceinline__ void attn_body(const u16* __restrict__ Qb, const u16* __restrict__ Kn, const u16* __restrict__ Kr,
;                                           u16* __restrict__ Ob, char* lds, int tid, const float* __restrict__ gq_, const float* __restrict__ tab_, int qpos0, float negM) {
;     ...
; #pragma unroll
;     for (int d0 = 0; d0 < 8; ++d0) {
;       const f32x4 g0 = *reinterpret_cast<const f32x4*>(gq + d0 * 16), g1 = *reinterpret_cast<const f32x4*>(gq + d0 * 16 + 4);
;       const u32x4 w = qw[d0];
;       const u32x4 o = {cvtpk(bflo(w[0]) * rq * g0[0], bfhi(w[0]) * rq * g0[1]), cvtpk(bflo(w[1]) * rq * g0[2], bfhi(w[1]) * rq * g0[3]),
;                        cvtpk(bflo(w[2]) * rq * g1[0], bfhi(w[2]) * rq * g1[1]), cvtpk(bflo(w[3]) * rq * g1[2], bfhi(w[3]) * rq * g1[3])};
;       qr[d0] = *reinterpret_cast<const bf16x8*>(&o); }
;     const float* tcp = tab_ + (size_t)(qpos0 + wid * 32 + r32) * 32 + hi * 8; const float* tsp = tcp + SEQ * 32;
; #pragma unroll
;     for (int dd = 0; dd < 2; ++dd) {
;       float x1[8], x2[8], c_[8], s_[8];
;       { const f32x4 ga = *reinterpret_cast<const f32x4*>(gq + 128 + dd * 16), gb = *reinterpret_cast<const f32x4*>(gq + 128 + dd * 16 + 4);
;         const f32x4 gc = *reinterpret_cast<const f32x4*>(gq + 160 + dd * 16), gd = *reinterpret_cast<const f32x4*>(gq + 160 + dd * 16 + 4);
;         const f32x4 ca = *reinterpret_cast<const f32x4*>(tcp + dd * 16), cb = *reinterpret_cast<const f32x4*>(tcp + dd * 16 + 4);
;         const f32x4 sa = *reinterpret_cast<const f32x4*>(tsp + dd * 16), sb = *reinterpret_cast<const f32x4*>(tsp + dd * 16 + 4);
	v_mul_f32_e32 v21, v28, v21
	v_mul_f32_e32 v28, v20, v133
	v_mul_f32_e32 v28, v29, v28
	s_nop 0
	v_cvt_pk_bf16_f32 v128, v21, v28
	v_mul_f32_e32 v21, v20, v154
	v_mul_f32_e32 v21, v30, v21
	v_mul_f32_e32 v28, v20, v155
	v_mul_f32_e32 v28, v31, v28
	s_nop 0
	v_cvt_pk_bf16_f32 v129, v21, v28
	v_mul_f32_e32 v21, v20, v162
	ds_read_b128 v[154:157], v254 offset:272
	ds_read_b128 v[158:161], v254 offset:256
	v_mul_f32_e32 v21, v24, v21
	v_mul_f32_e32 v24, v20, v163
	v_mul_f32_e32 v24, v25, v24
	s_nop 0
	v_cvt_pk_bf16_f32 v130, v21, v24
	v_mul_f32_e32 v24, v20, v165
	v_mul_f32_e32 v21, v20, v164
	v_mul_f32_e32 v24, v27, v24
	v_mul_f32_e32 v21, v26, v21
	s_nop 0
	v_cvt_pk_bf16_f32 v131, v21, v24
	v_mul_f32_e32 v24, v20, v167
	v_mul_f32_e32 v21, v20, v166
	v_mul_f32_e32 v24, v139, v24
	v_mul_f32_e32 v21, v138, v21
	s_nop 0
	v_cvt_pk_bf16_f32 v132, v21, v24
	v_mul_f32_e32 v24, v20, v169
	v_mul_f32_e32 v21, v20, v168
	v_mul_f32_e32 v24, v141, v24
	v_mul_f32_e32 v21, v140, v21
	s_nop 0
	v_cvt_pk_bf16_f32 v133, v21, v24
	ds_read_b128 v[24:27], v254 offset:336
	ds_read_b128 v[28:31], v254 offset:320
	v_mul_f32_e32 v21, v20, v126
	v_mul_f32_e32 v21, v134, v21
	v_mul_f32_e32 v59, v20, v125
	v_mul_f32_e32 v59, v135, v59
	s_nop 0
	v_cvt_pk_bf16_f32 v134, v21, v59
	v_mul_f32_e32 v21, v20, v170
	v_mul_f32_e32 v21, v136, v21
	v_mul_f32_e32 v59, v20, v127
	v_mul_f32_e32 v59, v137, v59
	s_nop 0
	v_cvt_pk_bf16_f32 v135, v21, v59
	v_mul_f32_e32 v21, v20, v171
	v_mul_f32_e32 v59, v20, v172
	ds_read_b128 v[162:165], v254 offset:400
	ds_read_b128 v[166:169], v254 offset:384
	v_lshl_add_u64 v[66:67], v[68:69], 0, s[12:13]
	v_and_b32_e32 v209, 63, v96
	v_and_b32_e32 v206, 31, v96
	v_mov_b32_e32 v33, v177
	s_mov_b32 s50, 0
	v_mul_f32_e32 v21, v21, v142
	v_mul_f32_e32 v59, v59, v143
	s_nop 0
	v_cvt_pk_bf16_f32 v136, v21, v59
	v_mul_f32_e32 v21, v20, v173
	v_mul_f32_e32 v21, v21, v144
	v_mul_f32_e32 v59, v20, v174
	v_mul_f32_e32 v59, v59, v145
	s_nop 0
	v_cvt_pk_bf16_f32 v137, v21, v59
	v_mul_f32_e32 v21, v20, v175
	v_mul_f32_e32 v16, v21, v16
	v_mul_f32_e32 v21, v20, v178
	v_mul_f32_e32 v17, v21, v17
	s_nop 0
	v_cvt_pk_bf16_f32 v138, v16, v17
	v_mul_f32_e32 v16, v20, v118
	v_mul_f32_e32 v16, v16, v18
	v_mul_f32_e32 v17, v20, v117
	v_mul_f32_e32 v17, v17, v19
	s_nop 0
	v_cvt_pk_bf16_f32 v139, v16, v17
	v_mul_f32_e32 v16, v20, v120
	v_mul_f32_e32 v16, v16, v150
	v_mul_f32_e32 v17, v20, v119
	v_mul_f32_e32 v17, v17, v151
	s_nop 0
	v_cvt_pk_bf16_f32 v140, v16, v17
	v_mul_f32_e32 v16, v20, v122
	v_mul_f32_e32 v16, v16, v152
	v_mul_f32_e32 v17, v20, v121
	v_mul_f32_e32 v17, v17, v153
	s_nop 0
	v_cvt_pk_bf16_f32 v141, v16, v17
	v_mul_f32_e32 v16, v20, v124
	v_mul_f32_e32 v16, v16, v146
	v_mul_f32_e32 v17, v20, v123
	v_mul_f32_e32 v17, v17, v147
	s_nop 0
	v_cvt_pk_bf16_f32 v142, v16, v17
	v_mul_f32_e32 v16, v20, v111
	v_mul_f32_e32 v16, v16, v148
	v_mul_f32_e32 v17, v20, v110
	v_mul_f32_e32 v17, v17, v149
	s_nop 0
	v_cvt_pk_bf16_f32 v143, v16, v17
	v_mul_f32_e32 v16, v20, v113
	s_waitcnt vmcnt(0) lgkmcnt(0)
	v_mul_f32_e32 v16, v16, v158
	v_mul_f32_e32 v17, v20, v112
	v_mul_f32_e32 v17, v17, v159
	s_nop 0
	v_cvt_pk_bf16_f32 v144, v16, v17
	v_mul_f32_e32 v16, v20, v115
	v_mul_f32_e32 v16, v16, v160
	v_mul_f32_e32 v17, v20, v114
	ds_read_b128 v[118:121], v254 offset:464
	ds_read_b128 v[122:125], v254 offset:448
	v_mul_f32_e32 v17, v17, v161
	s_nop 0
	v_cvt_pk_bf16_f32 v145, v16, v17
	v_mul_f32_e32 v16, v20, v116
	v_mul_f32_e32 v16, v16, v154
	v_mul_f32_e32 v17, v20, v90
	v_mul_f32_e32 v17, v17, v155
	s_nop 0
	v_cvt_pk_bf16_f32 v146, v16, v17
	v_mul_f32_e32 v16, v20, v98
	v_mul_f32_e32 v16, v16, v156
	v_mul_f32_e32 v17, v20, v94
	v_mul_f32_e32 v17, v17, v157
	s_nop 0
	v_cvt_pk_bf16_f32 v147, v16, v17
	v_mul_f32_e32 v16, v20, v103
	v_mul_f32_e32 v16, v16, v28
	v_mul_f32_e32 v17, v20, v99
	v_mul_f32_e32 v17, v17, v29
	s_nop 0
	v_cvt_pk_bf16_f32 v148, v16, v17
	v_mul_f32_e32 v16, v20, v106
	ds_read_b128 v[110:113], v254 offset:656
	ds_read_b128 v[114:117], v254 offset:640
	ds_read_b128 v[170:173], v254 offset:528
	ds_read_b128 v[178:181], v254 offset:512
	v_mul_f32_e32 v16, v16, v30
	v_mul_f32_e32 v17, v20, v104
	v_mul_f32_e32 v17, v17, v31
	s_nop 0
	v_cvt_pk_bf16_f32 v149, v16, v17
	v_mul_f32_e32 v16, v20, v108
	v_mul_f32_e32 v16, v16, v24
	v_mul_f32_e32 v17, v20, v107
	v_add_co_u32_e32 v98, vcc, s78, v68
	v_mul_f32_e32 v17, v17, v25
	s_nop 0
	v_cvt_pk_bf16_f32 v150, v16, v17
	v_mul_f32_e32 v16, v20, v109
	v_addc_co_u32_e32 v99, vcc, 0, v69, vcc
	v_mul_f32_e32 v21, v16, v26
	global_load_dwordx4 v[28:31], v[98:99], off
	global_load_dwordx4 v[16:19], v[68:69], off offset:16
	global_load_dwordx4 v[106:109], v[68:69], off
	v_mul_f32_e32 v24, v20, v82
	v_mul_f32_e32 v24, v24, v27
	s_nop 0
	v_cvt_pk_bf16_f32 v151, v21, v24
	v_mul_f32_e32 v21, v20, v84
	v_mul_f32_e32 v21, v21, v166
	v_mul_f32_e32 v24, v20, v83
	v_mul_f32_e32 v24, v24, v167
	s_nop 0
	v_cvt_pk_bf16_f32 v152, v21, v24
	v_mul_f32_e32 v21, v20, v86
	v_mul_f32_e32 v21, v21, v168
	v_mul_f32_e32 v24, v20, v85
	v_mul_f32_e32 v24, v24, v169
	s_nop 0
	v_cvt_pk_bf16_f32 v153, v21, v24
	v_mul_f32_e32 v21, v20, v88
	v_mul_f32_e32 v21, v21, v162
	v_mul_f32_e32 v24, v20, v87
	v_mul_f32_e32 v24, v24, v163
	s_nop 0
	v_cvt_pk_bf16_f32 v154, v21, v24
	v_mul_f32_e32 v21, v20, v91
	v_mul_f32_e32 v21, v21, v164
	v_mul_f32_e32 v24, v20, v89
	v_mul_f32_e32 v24, v24, v165
	s_nop 0
	v_cvt_pk_bf16_f32 v155, v21, v24
	v_mul_f32_e32 v21, v20, v95
	v_mul_f32_e32 v24, v20, v92
	v_mul_f32_e32 v59, v20, v93
	s_waitcnt vmcnt(0) lgkmcnt(0)
; __device__ __forceinline__ void attn_body(const u16* __restrict__ Qb, const u16* __restrict__ Kn, const u16* __restrict__ Kr,
;                                           u16* __restrict__ Ob, char* lds, int tid, const float* __restrict__ gq_, const float* __restrict__ tab_, int qpos0, float negM) {
;     ...
;     const float* tcp = tab_ + (size_t)(qpos0 + wid * 32 + r32) * 32 + hi * 8; const float* tsp = tcp + SEQ * 32;
; #pragma unroll
;     for (int dd = 0; dd < 2; ++dd) {
;       float x1[8], x2[8], c_[8], s_[8];
;       { const f32x4 ga = *reinterpret_cast<const f32x4*>(gq + 128 + dd * 16), gb = *reinterpret_cast<const f32x4*>(gq + 128 + dd * 16 + 4);
;         const f32x4 gc = *reinterpret_cast<const f32x4*>(gq + 160 + dd * 16), gd = *reinterpret_cast<const f32x4*>(gq + 160 + dd * 16 + 4);
;         const f32x4 ca = *reinterpret_cast<const f32x4*>(tcp + dd * 16), cb = *reinterpret_cast<const f32x4*>(tcp + dd * 16 + 4);
;         const f32x4 sa = *reinterpret_cast<const f32x4*>(tsp + dd * 16), sb = *reinterpret_cast<const f32x4*>(tsp + dd * 16 + 4);
;         const u32x4 w1 = qw[8 + dd], w2 = qw[10 + dd];
; #pragma unroll
;         for (int e = 0; e < 4; ++e) {
;           const float g1lo = e < 2 ? ga[2 * e] : gb[2 * e - 4], g1hi = e < 2 ? ga[2 * e + 1] : gb[2 * e - 3];
;           const float g2lo = e < 2 ? gc[2 * e] : gd[2 * e - 4], g2hi = e < 2 ? gc[2 * e + 1] : gd[2 * e - 3];
;           x1[2 * e] = bflo(w1[e]) * rq * g1lo; x1[2 * e + 1] = bfhi(w1[e]) * rq * g1hi;
;           x2[2 * e] = bflo(w2[e]) * rq * g2lo; x2[2 * e + 1] = bfhi(w2[e]) * rq * g2hi;
;           c_[2 * e] = e < 2 ? ca[2 * e] : cb[2 * e - 4]; c_[2 * e + 1] = e < 2 ? ca[2 * e + 1] : cb[2 * e - 3];
;           s_[2 * e] = e < 2 ? sa[2 * e] : sb[2 * e - 4]; s_[2 * e + 1] = e < 2 ? sa[2 * e + 1] : sb[2 * e - 3]; } }
;       float y1[8], y2[8];
; #pragma unroll
;       for (int e = 0; e < 8; ++e) { y1[e] = x1[e] * c_[e] - x2[e] * s_[e]; y2[e] = x2[e] * c_[e] + x1[e] * s_[e]; }
;       const u32x4 o1 = {cvtpk(y1[0], y1[1]), cvtpk(y1[2], y1[3]), cvtpk(y1[4], y1[5]), cvtpk(y1[6], y1[7])};
;       const u32x4 o2 = {cvtpk(y2[0], y2[1]), cvtpk(y2[2], y2[3]), cvtpk(y2[4], y2[5]), cvtpk(y2[6], y2[7])};
;       qr[8 + dd] = *reinterpret_cast<const bf16x8*>(&o1); qr[10 + dd] = *reinterpret_cast<const bf16x8*>(&o2); }
	v_mul_f32_e32 v21, v21, v122
	v_mul_f32_e32 v24, v24, v123
	s_nop 0
	v_cvt_pk_bf16_f32 v156, v21, v24
	v_mul_f32_e32 v21, v20, v100
	v_mul_f32_e32 v21, v21, v124
	global_load_dwordx4 v[24:27], v[78:79], off offset:16
	v_mul_f32_e32 v59, v59, v125
	s_nop 0
	v_cvt_pk_bf16_f32 v157, v21, v59
	v_mul_f32_e32 v21, v20, v101
	v_mul_f32_e32 v21, v21, v118
	v_mul_f32_e32 v59, v20, v97
	v_mul_f32_e32 v59, v59, v119
	s_nop 0
	v_cvt_pk_bf16_f32 v158, v21, v59
	v_mul_f32_e32 v21, v20, v105
	v_mul_f32_e32 v21, v21, v120
	v_pk_mul_f32 v[74:75], v[20:21], v[74:75] op_sel_hi:[0,1]
	v_mul_f32_e32 v59, v20, v102
	v_pk_mul_f32 v[70:71], v[20:21], v[70:71] op_sel_hi:[0,1]
	v_mul_f32_e32 v59, v59, v121
	v_mov_b32_e32 v79, v178
	v_mov_b32_e32 v178, v115
	v_pk_mul_f32 v[90:91], v[74:75], v[178:179]
	v_mov_b32_e32 v75, v180
	v_mov_b32_e32 v180, v117
	v_pk_mul_f32 v[76:77], v[20:21], v[76:77] op_sel_hi:[0,1]
	v_mov_b32_e32 v78, v114
	v_pk_mul_f32 v[72:73], v[20:21], v[72:73] op_sel_hi:[0,1]
	v_mov_b32_e32 v74, v116
	v_pk_mul_f32 v[100:101], v[70:71], v[180:181]
	v_pk_mul_f32 v[64:65], v[20:21], v[64:65] op_sel_hi:[0,1]
	v_mov_b32_e32 v70, v110
	v_mov_b32_e32 v71, v170
	s_nop 0
	v_cvt_pk_bf16_f32 v159, v21, v59
	v_pk_mul_f32 v[78:79], v[76:77], v[78:79]
	v_pk_mul_f32 v[94:95], v[72:73], v[74:75]
	v_pk_mul_f32 v[102:103], v[64:65], v[70:71]
	ds_read_b128 v[70:73], v254 offset:720
	ds_read_b128 v[74:77], v254 offset:704
	ds_read_b128 v[82:85], v254 offset:592
	ds_read_b128 v[86:89], v254 offset:576
	v_pk_mul_f32 v[58:59], v[20:21], v[62:63] op_sel_hi:[0,1]
	v_mov_b32_e32 v62, v112
	v_mov_b32_e32 v63, v172
	v_pk_mul_f32 v[104:105], v[58:59], v[62:63]
	v_mov_b32_e32 v62, v28
	v_mov_b32_e32 v63, v106
	v_pk_mul_f32 v[62:63], v[78:79], v[62:63]
	v_pk_mul_f32 v[22:23], v[20:21], v[22:23] op_sel_hi:[0,1]
	v_pk_mul_f32 v[58:59], v[20:21], v[60:61] op_sel_hi:[0,1]
	v_sub_f32_e32 v21, v63, v62
	v_mov_b32_e32 v62, v106
	v_mov_b32_e32 v63, v28
	v_pk_mul_f32 v[62:63], v[78:79], v[62:63]
	v_mov_b32_e32 v106, v29
	v_mov_b32_e32 v172, v113
	v_add_f32_e32 v78, v62, v63
	v_pk_mul_f32 v[62:63], v[90:91], v[106:107]
	v_mov_b32_e32 v28, v107
	v_mov_b32_e32 v170, v111
	v_pk_mul_f32 v[110:111], v[58:59], v[172:173]
	global_load_dwordx4 v[58:61], v[98:99], off offset:64
	v_sub_f32_e32 v79, v63, v62
	v_pk_mul_f32 v[28:29], v[90:91], v[28:29]
	global_load_dwordx4 v[62:65], v[68:69], off offset:80
	global_load_dwordx4 v[90:93], v[68:69], off offset:64
	v_add_f32_e32 v97, v28, v29
	v_mov_b32_e32 v28, v30
	v_mov_b32_e32 v29, v108
	v_pk_mul_f32 v[28:29], v[94:95], v[28:29]
	v_pk_mul_f32 v[22:23], v[22:23], v[170:171]
	v_sub_f32_e32 v68, v29, v28
	v_mov_b32_e32 v28, v108
	v_mov_b32_e32 v29, v30
	v_pk_mul_f32 v[28:29], v[94:95], v[28:29]
	v_mov_b32_e32 v108, v31
	v_add_f32_e32 v69, v28, v29
	v_pk_mul_f32 v[28:29], v[100:101], v[108:109]
	v_mov_b32_e32 v30, v109
	v_sub_f32_e32 v94, v29, v28
	v_pk_mul_f32 v[28:29], v[100:101], v[30:31]
	s_nop 0
	v_cvt_pk_bf16_f32 v164, v21, v79
	v_pk_mul_f32 v[46:47], v[20:21], v[46:47] op_sel_hi:[0,1]
	v_add_f32_e32 v95, v28, v29
	global_load_dwordx4 v[28:31], v[66:67], off offset:16
	v_mov_b32_e32 v67, v16
	v_pk_mul_f32 v[44:45], v[20:21], v[44:45] op_sel_hi:[0,1]
	s_waitcnt vmcnt(0) lgkmcnt(0)
	s_nop 0
	v_cvt_pk_bf16_f32 v165, v68, v94
	s_nop 0
	v_cvt_pk_bf16_f32 v160, v78, v97
	s_waitcnt vmcnt(0) lgkmcnt(0)
	v_mov_b32_e32 v66, v24
	v_pk_mul_f32 v[66:67], v[102:103], v[66:67]
	s_nop 0
	v_cvt_pk_bf16_f32 v161, v69, v95
	s_barrier
	v_sub_f32_e32 v98, v67, v66
	v_mov_b32_e32 v66, v16
	v_mov_b32_e32 v67, v24
	v_pk_mul_f32 v[66:67], v[102:103], v[66:67]
	v_mov_b32_e32 v16, v25
	v_mov_b32_e32 v24, v17
	v_add_f32_e32 v99, v66, v67
	v_pk_mul_f32 v[66:67], v[22:23], v[16:17]
	v_pk_mul_f32 v[16:17], v[22:23], v[24:25]
	v_sub_f32_e32 v66, v67, v66
	v_add_f32_e32 v22, v16, v17
	v_mov_b32_e32 v16, v26
	v_mov_b32_e32 v17, v18
	v_pk_mul_f32 v[16:17], v[104:105], v[16:17]
	s_nop 0
	v_cvt_pk_bf16_f32 v162, v99, v22
	s_nop 0
	v_cvt_pk_bf16_f32 v166, v98, v66
	v_mov_b32_e32 v25, v88
	v_sub_f32_e32 v23, v17, v16
	v_mov_b32_e32 v16, v18
	v_mov_b32_e32 v17, v26
	v_pk_mul_f32 v[16:17], v[104:105], v[16:17]
	v_mov_b32_e32 v18, v27
	v_add_f32_e32 v24, v16, v17
	v_pk_mul_f32 v[16:17], v[110:111], v[18:19]
	v_mov_b32_e32 v26, v19
	v_sub_f32_e32 v18, v17, v16
	v_pk_mul_f32 v[16:17], v[110:111], v[26:27]
	s_nop 0
	v_cvt_pk_bf16_f32 v167, v23, v18
	v_mov_b32_e32 v18, v74
	v_add_f32_e32 v16, v16, v17
	s_nop 0
	v_cvt_pk_bf16_f32 v163, v24, v16
	v_pk_mul_f32 v[16:17], v[20:21], v[56:57] op_sel_hi:[0,1]
	v_mov_b32_e32 v19, v86
	v_pk_mul_f32 v[22:23], v[20:21], v[52:53] op_sel_hi:[0,1]
	v_mov_b32_e32 v24, v76
	v_pk_mul_f32 v[16:17], v[16:17], v[18:19]
	v_pk_mul_f32 v[18:19], v[20:21], v[54:55] op_sel_hi:[0,1]
	v_pk_mul_f32 v[22:23], v[22:23], v[24:25]
	v_pk_mul_f32 v[24:25], v[20:21], v[50:51] op_sel_hi:[0,1]
	v_pk_mul_f32 v[26:27], v[20:21], v[48:49] op_sel_hi:[0,1]
	v_mov_b32_e32 v48, v70
	v_mov_b32_e32 v49, v82
	v_pk_mul_f32 v[20:21], v[20:21], v[42:43] op_sel_hi:[0,1]
	v_mov_b32_e32 v42, v58
	v_mov_b32_e32 v43, v90
	v_pk_mul_f32 v[26:27], v[26:27], v[48:49]
	v_mov_b32_e32 v48, v72
	v_mov_b32_e32 v49, v84
	v_pk_mul_f32 v[42:43], v[16:17], v[42:43]
	v_mov_b32_e32 v86, v75
	v_pk_mul_f32 v[44:45], v[44:45], v[48:49]
	v_sub_f32_e32 v48, v43, v42
	v_mov_b32_e32 v42, v90
	v_mov_b32_e32 v43, v58
	v_pk_mul_f32 v[18:19], v[18:19], v[86:87]
	v_pk_mul_f32 v[16:17], v[16:17], v[42:43]
	v_mov_b32_e32 v90, v59
	v_add_f32_e32 v42, v16, v17
	v_pk_mul_f32 v[16:17], v[18:19], v[90:91]
	v_mov_b32_e32 v58, v91
	v_sub_f32_e32 v43, v17, v16
	v_pk_mul_f32 v[16:17], v[18:19], v[58:59]
	v_mov_b32_e32 v88, v77
; __device__ __forceinline__ int v_rd_base(int lane) { return ((lane & 3) << 3) | (((lane >> 2) & 3) << 6) | (((lane >> 4) & 1) << 5) | (((lane >> 5) & 1) << 8); }
; #define AISSUE(k0, soff) do { const char* kb_ = (const char*)Kn + (size_t)(k0) * 4096; const char* rb_ = (const char*)Kr + (size_t)(k0) * 1024; \
;     char* st_ = lds + (soff) + tid * 16; \
;     GLDS(kb_ + vkn0, st_ + KOFF); GLDS(kb_ + vkn1, st_ + KOFF + 8192); GLDS(rb_ + vkr, st_ + KOFF + KROPE_OFF); \
;     GLDS(kb_ + vv0, st_); GLDS(kb_ + vv1, st_ + 8192); } while (0)
; #define WAITV(n) asm volatile("s_waitcnt vmcnt(" #n ")" ::: "memory")
; #define TBAR() do { __builtin_amdgcn_s_barrier(); SBAR(); } while (0)
; __device__ __forceinline__ void qkt(f32x16& p0, f32x16& p1, const char* Ks, const bf16x8* qr, int r32, int hi, float negM) {
;     ...
;   const char* kn = Ks + r32 * 256; const int xn = r32 & 15;
; #pragma unroll
;   for (int d0 = 0; d0 < 8; ++d0) { const int off = ((d0 * 2 + hi) ^ xn) << 4;
;     bf16x8 b0 = *reinterpret_cast<const bf16x8*>(kn + off);
;     bf16x8 b1 = *reinterpret_cast<const bf16x8*>(kn + 32 * 256 + off);
;     p0 = __builtin_amdgcn_mfma_f32_32x32x16_bf16(b0, qr[d0], p0, 0, 0, 0);
;     p1 = __builtin_amdgcn_mfma_f32_32x32x16_bf16(b1, qr[d0], p1, 0, 0, 0); }
; __device__ __forceinline__ void attn_body(const u16* __restrict__ Qb, const u16* __restrict__ Kn, const u16* __restrict__ Kr,
;                                           u16* __restrict__ Ob, char* lds, int tid, const float* __restrict__ gq_, const float* __restrict__ tab_, int qpos0, float negM) {
;     ...
;       for (int e = 0; e < 8; ++e) { y1[e] = x1[e] * c_[e] - x2[e] * s_[e]; y2[e] = x2[e] * c_[e] + x1[e] * s_[e]; }
;       const u32x4 o1 = {cvtpk(y1[0], y1[1]), cvtpk(y1[2], y1[3]), cvtpk(y1[4], y1[5]), cvtpk(y1[6], y1[7])};
;       const u32x4 o2 = {cvtpk(y2[0], y2[1]), cvtpk(y2[2], y2[3]), cvtpk(y2[4], y2[5]), cvtpk(y2[6], y2[7])};
;       qr[8 + dd] = *reinterpret_cast<const bf16x8*>(&o1); qr[10 + dd] = *reinterpret_cast<const bf16x8*>(&o2); }
;   }
;   const int vrb = (int)(uintptr_t)lds + v_rd_base(lane);
;   f32x16 pA0, pA1, pB0, pB1; bf16x8 pa0, pa1, pa2, pa3; constexpr int NT = SEQ / KVBLK;
;   WAITV(0); TBAR();
;   AISSUE(KVBLK, STG);
;   qkt(pA0, pA1, lds + KOFF, qr, r32, hi, negM); partialSM(pA0);
	v_add_f32_e32 v18, v16, v17
	v_mov_b32_e32 v16, v60
	v_mov_b32_e32 v17, v92
	v_pk_mul_f32 v[16:17], v[22:23], v[16:17]
	v_pk_mul_f32 v[24:25], v[24:25], v[88:89]
	v_sub_f32_e32 v19, v17, v16
	v_mov_b32_e32 v16, v92
	v_mov_b32_e32 v17, v60
	v_pk_mul_f32 v[16:17], v[22:23], v[16:17]
	v_mov_b32_e32 v92, v61
	v_add_f32_e32 v22, v16, v17
	v_pk_mul_f32 v[16:17], v[24:25], v[92:93]
	v_mov_b32_e32 v60, v93
	v_sub_f32_e32 v23, v17, v16
	v_pk_mul_f32 v[16:17], v[24:25], v[60:61]
	v_mov_b32_e32 v82, v71
	v_add_f32_e32 v24, v16, v17
	v_mov_b32_e32 v16, v28
	v_mov_b32_e32 v17, v62
	v_pk_mul_f32 v[16:17], v[26:27], v[16:17]
	v_pk_mul_f32 v[46:47], v[46:47], v[82:83]
	v_sub_f32_e32 v25, v17, v16
	v_mov_b32_e32 v16, v62
	v_mov_b32_e32 v17, v28
	v_pk_mul_f32 v[16:17], v[26:27], v[16:17]
	v_mov_b32_e32 v62, v29
	v_add_f32_e32 v26, v16, v17
	v_pk_mul_f32 v[16:17], v[46:47], v[62:63]
	v_mov_b32_e32 v28, v63
	v_sub_f32_e32 v27, v17, v16
	v_pk_mul_f32 v[16:17], v[46:47], v[28:29]
	v_mov_b32_e32 v84, v73
	v_add_f32_e32 v28, v16, v17
	v_mov_b32_e32 v16, v30
	v_mov_b32_e32 v17, v64
	v_pk_mul_f32 v[16:17], v[44:45], v[16:17]
	v_pk_mul_f32 v[20:21], v[20:21], v[84:85]
	v_sub_f32_e32 v29, v17, v16
	v_mov_b32_e32 v16, v64
	v_mov_b32_e32 v17, v30
	v_pk_mul_f32 v[16:17], v[44:45], v[16:17]
	v_mov_b32_e32 v64, v31
	v_add_f32_e32 v44, v16, v17
	v_pk_mul_f32 v[16:17], v[20:21], v[64:65]
	v_mov_b32_e32 v30, v65
	v_sub_f32_e32 v45, v17, v16
	v_pk_mul_f32 v[16:17], v[20:21], v[30:31]
	s_nop 0
	v_cvt_pk_bf16_f32 v168, v42, v18
	v_lshlrev_b32_e32 v18, 1, v96
	v_add_f32_e32 v16, v16, v17
	v_lshlrev_b32_e32 v17, 4, v96
	s_nop 0
	v_cvt_pk_bf16_f32 v171, v44, v16
	v_lshlrev_b32_e32 v16, 3, v209
	v_and_b32_e32 v17, 0xc0, v17
	v_and_or_b32 v17, v16, 24, v17
	v_and_b32_e32 v18, 32, v18
	v_and_b32_e32 v16, 0x100, v16
	v_or3_b32 v212, v17, v18, v16
	s_nop 0
	v_cvt_pk_bf16_f32 v172, v48, v43
	s_nop 0
	v_cvt_pk_bf16_f32 v173, v19, v23
	s_nop 0
	v_cvt_pk_bf16_f32 v174, v25, v27
	s_nop 0
	v_cvt_pk_bf16_f32 v175, v29, v45
	s_nop 0
	v_cvt_pk_bf16_f32 v169, v22, v24
	s_nop 0
	v_cvt_pk_bf16_f32 v170, v26, v28
	v_add_u32_e32 v16, 0xe000, v211
	s_add_u32 s48, s48, 0x40000
	v_readfirstlane_b32 s51, v16
	v_add_u32_e32 v16, 0x10000, v211
	s_addc_u32 s49, s49, 0
	s_mov_b32 m0, s51
	v_readfirstlane_b32 s51, v16
	v_add_u32_e32 v19, 0x12000, v211
	global_load_lds_dwordx4 v176, s[48:49]
	s_mov_b32 m0, s51
	v_readfirstlane_b32 s51, v19
	v_add_u32_e32 v18, 0xa000, v211
	global_load_lds_dwordx4 v32, s[48:49]
	v_lshl_add_u64 v[16:17], v[40:41], 0, s[14:15]
	s_mov_b32 m0, s51
	v_readfirstlane_b32 s51, v18
	global_load_lds_dwordx4 v[16:17], off
	v_add_u32_e32 v16, 0xc000, v211
	s_mov_b32 m0, s51
	v_readfirstlane_b32 s51, v16
	global_load_lds_dwordx4 v80, s[48:49]
	s_mov_b32 m0, s51
	s_nop 0
	global_load_lds_dwordx4 v81, s[48:49]
	s_setprio 1
	v_bitop3_b32 v16, v207, v96, 15 bitop3:0x78
	v_lshlrev_b32_e32 v213, 8, v206
	v_lshlrev_b32_e32 v214, 4, v16
	v_or_b32_e32 v16, v213, v214
	ds_read_b128 v[40:43], v16 offset:16384
	ds_read_b128 v[44:47], v16 offset:24576
	v_and_b32_e32 v48, 15, v96
	v_lshlrev_b32_e32 v222, 7, v206
	s_waitcnt lgkmcnt(0)
	v_mfma_f32_32x32x16_bf16 v[16:31], v[40:43], v[128:131], v[0:15]
	v_bitop3_b32 v40, v207, v48, 2 bitop3:0x36
	v_lshlrev_b32_e32 v215, 4, v40
	v_mfma_f32_32x32x16_bf16 v[80:95], v[44:47], v[128:131], v[0:15]
	v_or_b32_e32 v44, v213, v215
	ds_read_b128 v[40:43], v44 offset:16384
	ds_read_b128 v[44:47], v44 offset:24576
	s_waitcnt lgkmcnt(0)
	v_mfma_f32_32x32x16_bf16 v[16:31], v[40:43], v[132:135], v[16:31]
	v_bitop3_b32 v40, v207, v48, 4 bitop3:0x36
	v_lshlrev_b32_e32 v216, 4, v40
	v_mfma_f32_32x32x16_bf16 v[80:95], v[44:47], v[132:135], v[80:95]
	v_or_b32_e32 v44, v213, v216
	ds_read_b128 v[40:43], v44 offset:16384
	ds_read_b128 v[44:47], v44 offset:24576
	s_waitcnt lgkmcnt(0)
	v_mfma_f32_32x32x16_bf16 v[16:31], v[40:43], v[136:139], v[16:31]
	v_bitop3_b32 v40, v207, v48, 6 bitop3:0x36
	v_lshlrev_b32_e32 v217, 4, v40
	v_mfma_f32_32x32x16_bf16 v[80:95], v[44:47], v[136:139], v[80:95]
	v_or_b32_e32 v44, v213, v217
	ds_read_b128 v[40:43], v44 offset:16384
	ds_read_b128 v[44:47], v44 offset:24576
	s_waitcnt lgkmcnt(0)
	v_mfma_f32_32x32x16_bf16 v[16:31], v[40:43], v[140:143], v[16:31]
	v_bitop3_b32 v40, v207, v48, 8 bitop3:0x36
	v_lshlrev_b32_e32 v218, 4, v40
	v_mfma_f32_32x32x16_bf16 v[80:95], v[44:47], v[140:143], v[80:95]
	v_or_b32_e32 v44, v213, v218
	ds_read_b128 v[40:43], v44 offset:16384
	ds_read_b128 v[44:47], v44 offset:24576
	s_waitcnt lgkmcnt(0)
	v_mfma_f32_32x32x16_bf16 v[16:31], v[40:43], v[144:147], v[16:31]
	v_bitop3_b32 v40, v207, v48, 10 bitop3:0x36
	v_lshlrev_b32_e32 v219, 4, v40
	v_mfma_f32_32x32x16_bf16 v[80:95], v[44:47], v[144:147], v[80:95]
	v_or_b32_e32 v44, v213, v219
	ds_read_b128 v[40:43], v44 offset:16384
	ds_read_b128 v[44:47], v44 offset:24576
	s_waitcnt lgkmcnt(0)
; __device__ __forceinline__ void partialSM(f32x16& p0) {
; #pragma unroll
;   for (int r = 0; r < 16; ++r) p0[r] = __builtin_amdgcn_exp2f(p0[r]);
; }
; __device__ __forceinline__ void qkt(f32x16& p0, f32x16& p1, const char* Ks, const bf16x8* qr, int r32, int hi, float negM) {
;     ...
;   const char* kr = Ks + KROPE_OFF + r32 * 128; const int xr = (r32 >> 1) & 7;
; #pragma unroll
;   for (int d0 = 8; d0 < 12; ++d0) { const int off = (((d0 - 8) * 2 + hi) ^ xr) << 4;
;     bf16x8 b0 = *reinterpret_cast<const bf16x8*>(kr + off);
;     bf16x8 b1 = *reinterpret_cast<const bf16x8*>(kr + 32 * 128 + off);
;     p0 = __builtin_amdgcn_mfma_f32_32x32x16_bf16(b0, qr[d0], p0, 0, 0, 0);
;     p1 = __builtin_amdgcn_mfma_f32_32x32x16_bf16(b1, qr[d0], p1, 0, 0, 0); }
;   __builtin_amdgcn_s_setprio(0);
	v_mfma_f32_32x32x16_bf16 v[16:31], v[40:43], v[148:151], v[16:31]
	v_bitop3_b32 v40, v207, v48, 12 bitop3:0x36
	v_lshlrev_b32_e32 v220, 4, v40
	v_mfma_f32_32x32x16_bf16 v[80:95], v[44:47], v[148:151], v[80:95]
	v_or_b32_e32 v44, v213, v220
	ds_read_b128 v[40:43], v44 offset:16384
	ds_read_b128 v[44:47], v44 offset:24576
	s_waitcnt lgkmcnt(0)
	v_mfma_f32_32x32x16_bf16 v[16:31], v[40:43], v[152:155], v[16:31]
	v_bitop3_b32 v40, v207, v48, 14 bitop3:0x36
	v_lshlrev_b32_e32 v221, 4, v40
	v_bfe_u32 v48, v96, 1, 3
	v_mfma_f32_32x32x16_bf16 v[80:95], v[44:47], v[152:155], v[80:95]
	v_or_b32_e32 v44, v213, v221
	ds_read_b128 v[40:43], v44 offset:16384
	ds_read_b128 v[44:47], v44 offset:24576
	s_waitcnt lgkmcnt(0)
	v_mfma_f32_32x32x16_bf16 v[16:31], v[40:43], v[156:159], v[16:31]
	v_lshrrev_b32_e32 v40, 1, v96
	v_bitop3_b32 v40, v207, v40, 7 bitop3:0x78
	v_lshlrev_b32_e32 v223, 4, v40
	v_mfma_f32_32x32x16_bf16 v[80:95], v[44:47], v[156:159], v[80:95]
	v_or_b32_e32 v44, v222, v223
	ds_read_b128 v[40:43], v44 offset:32768
	ds_read_b128 v[44:47], v44 offset:36864
	s_waitcnt lgkmcnt(0)
	v_mfma_f32_32x32x16_bf16 v[16:31], v[40:43], v[164:167], v[16:31]
	v_bitop3_b32 v40, v207, v48, 2 bitop3:0x36
	v_lshlrev_b32_e32 v224, 4, v40
	v_mfma_f32_32x32x16_bf16 v[80:95], v[44:47], v[164:167], v[80:95]
	v_or_b32_e32 v44, v222, v224
	ds_read_b128 v[40:43], v44 offset:32768
	ds_read_b128 v[44:47], v44 offset:36864
	s_waitcnt lgkmcnt(0)
	v_mfma_f32_32x32x16_bf16 v[16:31], v[40:43], v[172:175], v[16:31]
	v_bitop3_b32 v40, v207, v48, 4 bitop3:0x36
	v_lshlrev_b32_e32 v225, 4, v40
	v_mfma_f32_32x32x16_bf16 v[80:95], v[44:47], v[172:175], v[80:95]
	v_or_b32_e32 v44, v222, v225
	ds_read_b128 v[40:43], v44 offset:32768
	ds_read_b128 v[44:47], v44 offset:36864
	s_waitcnt lgkmcnt(0)
	v_mfma_f32_32x32x16_bf16 v[16:31], v[40:43], v[160:163], v[16:31]
	v_bitop3_b32 v40, v207, v48, 6 bitop3:0x36
	v_lshlrev_b32_e32 v226, 4, v40
	v_mfma_f32_32x32x16_bf16 v[80:95], v[44:47], v[160:163], v[80:95]
	v_or_b32_e32 v44, v222, v226
	ds_read_b128 v[40:43], v44 offset:32768
	ds_read_b128 v[44:47], v44 offset:36864
	s_waitcnt lgkmcnt(0)
	v_mfma_f32_32x32x16_bf16 v[16:31], v[40:43], v[168:171], v[16:31]
	v_mfma_f32_32x32x16_bf16 v[80:95], v[44:47], v[168:171], v[80:95]
	s_setprio 0
	s_nop 9
	v_exp_f32_e32 v240, v16
	v_exp_f32_e32 v242, v17
	v_exp_f32_e32 v238, v18
	v_exp_f32_e32 v241, v19
	v_exp_f32_e32 v236, v20
	v_exp_f32_e32 v239, v21
	v_exp_f32_e32 v235, v22
	v_exp_f32_e32 v237, v23
	v_exp_f32_e32 v232, v24
	v_exp_f32_e32 v234, v25
	v_exp_f32_e32 v230, v26
	v_exp_f32_e32 v233, v27
	v_exp_f32_e32 v228, v28
	v_exp_f32_e32 v231, v29
	v_exp_f32_e32 v227, v30
	v_exp_f32_e32 v229, v31
	s_or_b32 s48, s63, s80
	s_mov_b32 s49, s64
	v_lshl_add_u64 v[178:179], s[48:49], 0, v[34:35]
	s_or_b32 s48, s59, s79
	s_mov_b32 s49, s60
	v_lshl_add_u64 v[180:181], s[48:49], 0, v[38:39]
	v_lshl_add_u64 v[182:183], s[48:49], 0, v[36:37]
	v_lshl_add_u64 v[184:185], s[48:49], 0, v[176:177]
	v_lshl_add_u64 v[186:187], s[48:49], 0, v[32:33]
	s_mov_b32 s54, 0x14000
	s_mov_b32 s48, -1
	s_mov_b32 s49, 0xa000
	v_mov_b32_e32 v176, 0
	v_mov_b32_e32 v16, 0
	v_mov_b32_e32 v17, v177
	v_mov_b32_e32 v18, v177
	v_mov_b32_e32 v19, v177
	v_mov_b32_e32 v20, v177
	v_mov_b32_e32 v21, v177
	v_mov_b32_e32 v22, v177
	v_mov_b32_e32 v23, v177
	v_mov_b32_e32 v24, v177
	v_mov_b32_e32 v25, v177
	v_mov_b32_e32 v26, v177
	v_mov_b32_e32 v27, v177
	v_mov_b32_e32 v28, v177
	v_mov_b32_e32 v29, v177
	v_mov_b32_e32 v30, v177
	v_mov_b32_e32 v31, v177
	v_mov_b32_e32 v32, 0
	v_mov_b32_e32 v34, v177
	v_mov_b32_e32 v36, v177
	v_mov_b32_e32 v38, v177
	v_mov_b32_e32 v40, v177
	v_mov_b32_e32 v41, v177
	v_mov_b32_e32 v42, v177
	v_mov_b32_e32 v43, v177
	v_mov_b32_e32 v44, v177
	v_mov_b32_e32 v45, v177
	v_mov_b32_e32 v46, v177
	v_mov_b32_e32 v47, v177
	v_mov_b32_e32 v48, 0
	v_mov_b32_e32 v49, v177
	v_mov_b32_e32 v50, v177
	v_mov_b32_e32 v51, v177
	v_mov_b32_e32 v52, v177
	v_mov_b32_e32 v53, v177
	v_mov_b32_e32 v54, v177
	v_mov_b32_e32 v55, v177
	v_mov_b32_e32 v56, v177
	v_mov_b32_e32 v57, v177
	v_mov_b32_e32 v58, v177
	v_mov_b32_e32 v59, v177
	v_mov_b32_e32 v60, v177
	v_mov_b32_e32 v61, v177
	v_mov_b32_e32 v62, v177
	v_mov_b32_e32 v63, v177
	v_mov_b32_e32 v64, 0
	v_mov_b32_e32 v65, v177
	v_mov_b32_e32 v66, v177
	v_mov_b32_e32 v67, v177
	v_mov_b32_e32 v68, v177
	v_mov_b32_e32 v69, v177
	v_mov_b32_e32 v70, v177
	v_mov_b32_e32 v71, v177
	v_mov_b32_e32 v72, v177
	v_mov_b32_e32 v73, v177
	v_mov_b32_e32 v74, v177
	v_mov_b32_e32 v75, v177
	v_mov_b32_e32 v76, v177
	v_mov_b32_e32 v77, v177
	v_mov_b32_e32 v78, v177
	v_mov_b32_e32 v79, v177
